# rwc per-row v values moved to a padded (144 B pitch) LDS area: producers' ds_write2_b32 no longer 8-way and the scanners' vv ds_read_b128 no longer 2-way bank conflicted
# speedup vs baseline: 1.0210x; 1.0011x over previous
; #define LAS __attribute__((address_space(3)))
; __device__ __forceinline__ int ltid(int wvs) { int t = (wvs << 6) | (int)__builtin_amdgcn_mbcnt_hi(~0u, __builtin_amdgcn_mbcnt_lo(~0u, 0u)); asm volatile("" : "+v"(t)); return t; }
; __device__ __forceinline__ int lbid() { int b = __builtin_amdgcn_workgroup_id_x(); asm volatile("" : "+s"(b)); return b; }
; __device__ __forceinline__ void phase_rwc(const int wvs, const Params& p, LAS unsigned char* lds, int layer, int wg0) {
;   const int wgi = lbid() - wg0; if (wgi < 0 || wgi >= NB * 48) return;
;   const int tid = ltid(wvs), wv = tid >> 6, lane = tid & 63;
;   const int qd = wgi / 48, chain = wgi - qd * 48, d = chain & 1, h = (chain >> 1) % 6, b = chain / 12; const int v0 = qd * 16;
;   constexpr int BUFSZ = 5 * 8192 + 2048, NBLK = TPB / 32, YOFF = 2 * BUFSZ, YSZ = 32 * 16 * 16 * 4;
;   hf* P = (hf*)(p.ws + OFF_BIG); const hf* RL = (const hf*)(p.ws + OFF_RL1); const float* INVN = (const float*)(p.ws + OFF_INVN);
;   const size_t tb = (size_t)b * TPB;
;     ...
;   if (wv >= 4) {
;     ...
;     const int rowl = wv * 4 + (lane >> 4), kg = lane & 15;
;     f32x4 S = {0.f, 0.f, 0.f, 0.f};
;     __syncthreads();
; #pragma unroll 2
;     for (int blk = 0; blk < NBLK; ++blk) {
;       LAS float* Wv = (LAS float*)(lds + (blk & 1) * BUFSZ) + kg * 4; LAS float* Vv = (LAS float*)(lds + (blk & 1) * BUFSZ) + 5 * 2048 + rowl;
;       LAS float* ypw = (LAS float*)(lds + YOFF + (blk & 1) * YSZ) + rowl * 16 + kg;
;       asm volatile("" : "+v"(Wv), "+v"(Vv), "+v"(ypw));
;       f32x4 w4 = *(const LAS f32x4*)(Wv), kk4 = *(const LAS f32x4*)(Wv + 2048), b4 = *(const LAS f32x4*)(Wv + 4096), kd4 = *(const LAS f32x4*)(Wv + 6144), r4 = *(const LAS f32x4*)(Wv + 8192); float vv = Vv[0];
;       f32x4 xw4 = *(const LAS f32x4*)(Wv + 64), xkk4 = *(const LAS f32x4*)(Wv + 2048 + 64), xb4 = *(const LAS f32x4*)(Wv + 4096 + 64), xkd4 = *(const LAS f32x4*)(Wv + 6144 + 64), xr4 = *(const LAS f32x4*)(Wv + 8192 + 64); float xvv = Vv[16];
.LBB0_1240:
	s_mov_b64 s[4:5], s[0:1]
	s_mov_b32 s10, s28
	s_add_i32 s2, s10, 0xffffff10
	s_cmp_lt_u32 s2, 0xffffff40
	s_cbranch_scc1 .LBB0_1367
	v_mov_b32_e32 v25, v193
	s_nop 0
	v_ashrrev_i32_e32 v0, 6, v25
	v_cmp_gt_i32_e32 vcc, 4, v0
	v_and_b32_e32 v17, 15, v25
	s_and_saveexec_b64 s[6:7], vcc
	s_xor_b64 s[6:7], exec, s[6:7]
	s_cbranch_execz .LBB0_1248
	v_bfe_u32 v2, v25, 4, 2
	v_lshl_or_b32 v0, v0, 2, v2
	v_lshlrev_b32_e32 v2, 6, v0
	v_lshlrev_b32_e32 v3, 2, v17
	v_readlane_b32 s2, v254, 5
	v_lshlrev_b32_e32 v0, 2, v0
	v_lshl_add_u32 v69, v17, 4, 0
	v_add3_u32 v68, s2, v2, v3
	v_add_u32_e32 v2, 0, v0
	v_add_u32_e32 v70, 0xa000, v2
	v_readlane_b32 s2, v254, 6
	v_mov_b32_e32 v2, v1
	v_mov_b32_e32 v3, v1
	v_add_u32_e32 v72, s2, v0
	v_mov_b32_e32 v0, v1
	v_mov_b64_e32 v[4:5], v[2:3]
	v_add_u32_e32 v71, 0xa800, v69
	v_add_u32_e32 v73, 0x8000, v68
	s_mov_b32 s8, 0
	v_mov_b64_e32 v[2:3], v[0:1]
	s_waitcnt lgkmcnt(0)
	s_barrier
	v_mov_b32_e32 v80, v69
	v_mov_b32_e32 v82, v68
	v_mov_b32_e32 v83, v71
	v_mov_b32_e32 v85, v73
	v_add_u32_e32 v81, 0xffff6000, v70
	v_mul_u32_u24_e32 v81, 36, v81
	v_add_u32_e32 v81, 0x25000, v81
	v_add_u32_e32 v84, 0x900, v81

.LBB0_1275:
	v_ashrrev_i32_e32 v11, 31, v10
	v_lshl_add_u64 v[10:11], s[16:17], 0, v[10:11]
	v_mov_b64_e32 v[32:33], s[24:25]
	v_mad_u64_u32 v[32:33], s[44:45], v10, s68, v[32:33]
	v_mov_b32_e32 v10, v33
	v_mad_u64_u32 v[10:11], s[44:45], v11, s68, v[10:11]
	v_mov_b32_e32 v33, v10
	v_lshl_add_u64 v[10:11], s[12:13], 1, v[32:33]
	s_lshl_b32 s44, s48, 5
	s_mov_b32 s45, s31
	v_lshl_add_u64 v[32:33], v[10:11], 0, s[44:45]
	v_lshlrev_b32_e32 v10, 1, v25
	v_and_b32_e32 v58, 14, v10
	v_lshlrev_b32_e32 v10, 1, v58
	v_mov_b32_e32 v11, v1
	v_lshl_add_u64 v[32:33], v[32:33], 0, v[10:11]
	global_load_dword v11, v[32:33], off offset:1536
	s_waitcnt vmcnt(8)
	v_cvt_f32_f16_e32 v32, v26
	v_cvt_f32_f16_sdwa v26, v26 dst_sel:DWORD dst_unused:UNUSED_PAD src0_sel:WORD_1
	v_cvt_f32_f16_sdwa v41, v22 dst_sel:DWORD dst_unused:UNUSED_PAD src0_sel:WORD_1
	v_cvt_f32_f16_e32 v40, v22
	v_cvt_f32_f16_sdwa v37, v28 dst_sel:DWORD dst_unused:UNUSED_PAD src0_sel:WORD_1
	v_mul_f32_e32 v22, 0xbfb8aa3b, v26
	v_cvt_f32_f16_e32 v36, v28
	v_exp_f32_e32 v33, v22
	v_cvt_f32_f16_e32 v22, v27
	v_cvt_f32_f16_sdwa v26, v27 dst_sel:DWORD dst_unused:UNUSED_PAD src0_sel:WORD_1
	v_cvt_f32_f16_sdwa v51, v29 dst_sel:DWORD dst_unused:UNUSED_PAD src0_sel:WORD_1
	v_cvt_f32_f16_e32 v50, v29
	s_waitcnt vmcnt(7)
	v_cvt_f32_f16_sdwa v49, v30 dst_sel:DWORD dst_unused:UNUSED_PAD src0_sel:WORD_1
	v_cvt_f32_f16_e32 v48, v30
	v_cvt_f32_f16_sdwa v57, v31 dst_sel:DWORD dst_unused:UNUSED_PAD src0_sel:WORD_1
	v_cvt_f32_f16_e32 v56, v31
	v_pk_mul_f32 v[34:35], v[2:3], v[36:37]
	v_mul_f32_e32 v22, 0xbfb8aa3b, v22
	s_waitcnt vmcnt(6)
	v_pk_mul_f32 v[44:45], v[24:25], v[34:35] op_sel_hi:[0,1]
	v_exp_f32_e32 v34, v22
	v_mul_f32_e32 v22, 0xbfb8aa3b, v26
	v_cvt_f32_f16_sdwa v43, v23 dst_sel:DWORD dst_unused:UNUSED_PAD src0_sel:WORD_1
	v_cvt_f32_f16_e32 v42, v23
	v_exp_f32_e32 v35, v22
	v_pk_mul_f32 v[22:23], v[4:5], v[50:51]
	v_mul_f32_e32 v28, 0xbfb8aa3b, v32
	v_pk_mul_f32 v[46:47], v[24:25], v[22:23] op_sel_hi:[0,1]
	v_xor_b32_e32 v22, 0x80000000, v48
	v_xor_b32_e32 v23, 0x80000000, v49
	v_xor_b32_e32 v26, 0x80000000, v56
	v_xor_b32_e32 v27, 0x80000000, v57
	v_exp_f32_e32 v32, v28
	v_pk_mul_f32 v[28:29], v[46:47], v[26:27]
	v_pk_mul_f32 v[26:27], v[44:45], v[22:23]
	v_pk_add_f32 v[22:23], v[48:49], -1.0 op_sel_hi:[1,0]
	v_lshlrev_b32_e32 v55, 2, v39
	v_pk_fma_f32 v[22:23], v[6:7], v[22:23], 1.0 op_sel_hi:[1,1,0]
	v_pk_add_f32 v[30:31], v[56:57], -1.0 op_sel_hi:[1,0]
	v_pk_mul_f32 v[48:49], v[22:23], v[36:37]
	s_waitcnt vmcnt(3)
	v_cvt_f32_f16_e32 v23, v14
	v_cvt_f32_f16_sdwa v14, v14 dst_sel:DWORD dst_unused:UNUSED_PAD src0_sel:WORD_1
	v_and_b32_e32 v22, 0xffffffc0, v55
	v_pk_fma_f32 v[30:31], v[8:9], v[30:31], 1.0 op_sel_hi:[1,1,0]
	v_lshlrev_b32_e32 v22, 2, v22
	v_pk_mul_f32 v[50:51], v[30:31], v[50:51]
	v_add3_u32 v55, 0, v38, v22
	v_cvt_f32_f16_sdwa v31, v12 dst_sel:DWORD dst_unused:UNUSED_PAD src0_sel:WORD_1
	v_cvt_f32_f16_e32 v30, v12
	v_mul_f32_e32 v12, 0xbfb8aa3b, v14
	ds_write_b128 v55, v[32:35]
	ds_write_b128 v55, v[44:47] offset:8192
	ds_write_b128 v55, v[26:29] offset:16384
	ds_write_b128 v55, v[48:51] offset:24576
	ds_write_b128 v55, v[40:43] offset:32768
	v_cvt_f32_f16_sdwa v41, v18 dst_sel:DWORD dst_unused:UNUSED_PAD src0_sel:WORD_1
	v_cvt_f32_f16_e32 v40, v18
	v_exp_f32_e32 v27, v12
	v_cvt_f32_f16_e32 v12, v15
	v_cvt_f32_f16_sdwa v14, v15 dst_sel:DWORD dst_unused:UNUSED_PAD src0_sel:WORD_1
	v_mul_f32_e32 v18, 0xbfb8aa3b, v23
	v_cvt_f32_f16_sdwa v45, v19 dst_sel:DWORD dst_unused:UNUSED_PAD src0_sel:WORD_1
	v_cvt_f32_f16_e32 v44, v19
	s_waitcnt vmcnt(2)
	v_cvt_f32_f16_sdwa v43, v20 dst_sel:DWORD dst_unused:UNUSED_PAD src0_sel:WORD_1
	v_cvt_f32_f16_e32 v42, v20
	v_exp_f32_e32 v26, v18
	v_pk_mul_f32 v[28:29], v[2:3], v[40:41]
	v_cvt_f32_f16_sdwa v19, v21 dst_sel:DWORD dst_unused:UNUSED_PAD src0_sel:WORD_1
	v_cvt_f32_f16_e32 v18, v21
	v_mul_f32_e32 v12, 0xbfb8aa3b, v12
	s_waitcnt vmcnt(1)
	v_pk_mul_f32 v[34:35], v[16:17], v[28:29] op_sel_hi:[0,1]
	v_exp_f32_e32 v28, v12
	v_mul_f32_e32 v12, 0xbfb8aa3b, v14
	v_exp_f32_e32 v29, v12
	v_cvt_f32_f16_sdwa v33, v13 dst_sel:DWORD dst_unused:UNUSED_PAD src0_sel:WORD_1
	v_cvt_f32_f16_e32 v32, v13
	v_pk_mul_f32 v[12:13], v[4:5], v[44:45]
	v_xor_b32_e32 v14, 0x80000000, v18
	v_pk_mul_f32 v[36:37], v[16:17], v[12:13] op_sel_hi:[0,1]
	v_xor_b32_e32 v12, 0x80000000, v42
	v_xor_b32_e32 v13, 0x80000000, v43
	v_xor_b32_e32 v15, 0x80000000, v19
	v_pk_add_f32 v[20:21], v[42:43], -1.0 op_sel_hi:[1,0]
	v_pk_add_f32 v[18:19], v[18:19], -1.0 op_sel_hi:[1,0]
	v_pk_mul_f32 v[12:13], v[34:35], v[12:13]
	v_pk_fma_f32 v[18:19], v[8:9], v[18:19], 1.0 op_sel_hi:[1,1,0]
	v_pk_fma_f32 v[42:43], v[6:7], v[20:21], 1.0 op_sel_hi:[1,1,0]
	v_pk_mul_f32 v[14:15], v[36:37], v[14:15]
	v_pk_mul_f32 v[20:21], v[18:19], v[44:45]
	v_pk_mul_f32 v[18:19], v[42:43], v[40:41]
	ds_write_b128 v55, v[26:29] offset:4096
	ds_write_b128 v55, v[34:37] offset:12288
	ds_write_b128 v55, v[12:15] offset:20480
	ds_write_b128 v55, v[18:21] offset:28672
	s_waitcnt vmcnt(0)
	v_cvt_f32_f16_e32 v12, v11
	v_cvt_f32_f16_sdwa v13, v11 dst_sel:DWORD dst_unused:UNUSED_PAD src0_sel:WORD_1
	v_lshl_or_b32 v14, v58, 5, v54
	v_mul_u32_u24_e32 v56, 0x90, v58
	v_lshl_add_u32 v56, v54, 2, v56
	v_add_u32_e32 v56, 0x25000, v56
	s_mov_b64 s[44:45], -1
	s_and_b64 vcc, exec, s[22:23]
	ds_write_b128 v55, v[30:33] offset:36864
	ds_write2_b32 v56, v12, v13 offset1:36
	s_cbranch_vccz .LBB0_1281
	s_movk_i32 s2, 0xdff
	v_cmp_lt_u32_e32 vcc, s2, v39
	s_and_saveexec_b64 s[44:45], vcc
	s_xor_b64 s[44:45], exec, s[44:45]
	v_sub_u32_e32 v12, 0x11df, v52
	s_andn2_saveexec_b64 s[44:45], s[44:45]
	v_sub_u32_e32 v12, 0xdf, v52
	s_or_b64 exec, exec, s[44:45]
	s_mov_b64 s[44:45], 0

; __device__ __forceinline__ void phase_rwc(const int wvs, const Params& p, LAS unsigned char* lds, int layer, int wg0) {
;     ...
;     RW_LOAD(0) RW_DERIVE(0) RW_LOAD(1)
;     __syncthreads();
; #pragma unroll 2
;     for (int blk = 0; blk < NBLK; ++blk) {
;       if (blk + 1 < NBLK) RW_DERIVE((blk + 1) & 1)
;       if (blk + 2 < NBLK) RW_LOAD(blk + 2)
.LBB0_1299:
	v_ashrrev_i32_e32 v13, 31, v12
	v_lshl_add_u64 v[12:13], s[16:17], 0, v[12:13]
	v_mov_b64_e32 v[18:19], s[24:25]
	v_mad_u64_u32 v[18:19], s[44:45], v12, s68, v[18:19]
	v_mov_b32_e32 v12, v19
	v_mad_u64_u32 v[12:13], s[44:45], v13, s68, v[12:13]
	s_lshl_b32 s2, s48, 4
	v_mov_b32_e32 v19, v12
	s_lshl_b32 s22, s2, 1
	s_mov_b32 s23, s31
	v_lshl_add_u64 v[12:13], v[18:19], 0, s[26:27]
	v_lshl_add_u64 v[12:13], v[12:13], 0, s[22:23]
	v_mov_b32_e32 v11, v1
	v_lshl_add_u64 v[12:13], v[12:13], 0, v[10:11]
	v_mov_b64_e32 v[84:85], v[12:13]
	global_load_dword v65, v[12:13], off offset:1536
	s_add_u32 s20, s20, s22
	s_addc_u32 s21, s21, 0
	v_lshlrev_b32_e32 v12, 1, v17
	v_mov_b32_e32 v13, v1
	v_lshl_add_u64 v[26:27], s[20:21], 0, v[12:13]
	v_readlane_b32 s2, v254, 7
	s_add_u32 s20, s24, s26
	s_addc_u32 s21, s25, s27
	v_add3_u32 v59, s2, v38, v22
	v_readlane_b32 s2, v254, 8
	v_lshlrev_b32_e32 v58, 6, v39
	v_lshlrev_b32_e32 v57, 6, v25
	v_add3_u32 v60, s2, v38, v22
	v_lshl_add_u64 v[38:39], s[20:21], 0, v[0:1]
	s_add_u32 s20, s20, s22
	v_readlane_b32 s2, v254, 6
	s_addc_u32 s21, s21, 0
	v_lshl_add_u64 v[40:41], s[20:21], 0, v[10:11]
	v_lshrrev_b32_e32 v61, 5, v14
	v_mul_u32_u24_e32 v61, 0x90, v61
	v_and_b32_e32 v99, 31, v14
	v_lshl_add_u32 v61, v99, 2, v61
	v_add_u32_e32 v61, 0x25900, v61
	v_sub_u32_e32 v62, 0x121f, v52
	v_sub_u32_e32 v63, 0x121f, v53
	v_sub_u32_e32 v64, 0x11bf, v54
	s_mov_b32 s24, 0
	s_mov_b32 s25, 0
	s_waitcnt lgkmcnt(0)
	s_barrier
	s_branch .LBB0_1302

; __device__ __forceinline__ void phase_rwc(const int wvs, const Params& p, LAS unsigned char* lds, int layer, int wg0) {
;     ...
;     for (int blk = 0; blk < NBLK; ++blk) {
;       if (blk + 1 < NBLK) RW_DERIVE((blk + 1) & 1)
;       if (blk + 2 < NBLK) RW_LOAD(blk + 2)
;       if (blk >= 1) RW_YOUT(blk - 1)
;       __syncthreads();
.LBB0_1302:
	s_waitcnt vmcnt(9)
	v_cvt_f32_f16_sdwa v21, v28 dst_sel:DWORD dst_unused:UNUSED_PAD src0_sel:WORD_1
	v_cvt_f32_f16_e32 v20, v28
	s_waitcnt vmcnt(7)
	v_cvt_f32_f16_sdwa v51, v36 dst_sel:DWORD dst_unused:UNUSED_PAD src0_sel:WORD_1
	v_cvt_f32_f16_e32 v50, v36
	v_cvt_f32_f16_sdwa v69, v37 dst_sel:DWORD dst_unused:UNUSED_PAD src0_sel:WORD_1
	v_pk_mul_f32 v[12:13], v[2:3], v[20:21]
	v_cvt_f32_f16_e32 v68, v37
	v_cvt_f32_f16_e32 v10, v32
	v_cvt_f32_f16_sdwa v11, v32 dst_sel:DWORD dst_unused:UNUSED_PAD src0_sel:WORD_1
	s_waitcnt vmcnt(1)
	v_pk_mul_f32 v[14:15], v[12:13], v[34:35] op_sel_hi:[1,0]
	v_cvt_f32_f16_e32 v12, v33
	v_cvt_f32_f16_sdwa v13, v33 dst_sel:DWORD dst_unused:UNUSED_PAD src0_sel:WORD_1
	v_cvt_f32_f16_sdwa v67, v29 dst_sel:DWORD dst_unused:UNUSED_PAD src0_sel:WORD_1
	v_cvt_f32_f16_e32 v66, v29
	v_xor_b32_e32 v22, 0x80000000, v50
	v_xor_b32_e32 v23, 0x80000000, v51
	v_xor_b32_e32 v24, 0x80000000, v68
	v_xor_b32_e32 v25, 0x80000000, v69
	v_pk_add_f32 v[50:51], v[50:51], -1.0 op_sel_hi:[1,0]
	v_pk_add_f32 v[68:69], v[68:69], -1.0 op_sel_hi:[1,0]
	v_mul_f32_e32 v10, 0xbfb8aa3b, v10
	v_mul_f32_e32 v11, 0xbfb8aa3b, v11
	v_mul_f32_e32 v12, 0xbfb8aa3b, v12
	v_mul_f32_e32 v13, 0xbfb8aa3b, v13
	v_pk_fma_f32 v[68:69], v[8:9], v[68:69], 1.0 op_sel_hi:[1,1,0]
	v_pk_fma_f32 v[50:51], v[6:7], v[50:51], 1.0 op_sel_hi:[1,1,0]
	v_exp_f32_e32 v10, v10
	v_exp_f32_e32 v11, v11
	v_cvt_f32_f16_sdwa v19, v30 dst_sel:DWORD dst_unused:UNUSED_PAD src0_sel:WORD_1
	v_cvt_f32_f16_e32 v18, v30
	v_exp_f32_e32 v12, v12
	v_exp_f32_e32 v13, v13
	v_pk_mul_f32 v[16:17], v[4:5], v[66:67]
	v_pk_mul_f32 v[68:69], v[68:69], v[66:67]
	v_pk_mul_f32 v[66:67], v[50:51], v[20:21]
	v_cvt_f32_f16_sdwa v21, v31 dst_sel:DWORD dst_unused:UNUSED_PAD src0_sel:WORD_1
	v_cvt_f32_f16_e32 v20, v31
	v_pk_mul_f32 v[16:17], v[16:17], v[34:35] op_sel_hi:[1,0]
	v_pk_mul_f32 v[22:23], v[14:15], v[22:23]
	v_pk_mul_f32 v[24:25], v[16:17], v[24:25]
	ds_write_b128 v55, v[10:13] offset:43008
	ds_write_b128 v55, v[14:17] offset:51200
	ds_write_b128 v55, v[22:25] offset:59392
	ds_write_b128 v60, v[18:21]
	v_cvt_f32_f16_sdwa v21, v42 dst_sel:DWORD dst_unused:UNUSED_PAD src0_sel:WORD_1
	v_cvt_f32_f16_e32 v20, v42
	v_cvt_f32_f16_e32 v10, v46
	v_cvt_f32_f16_sdwa v11, v46 dst_sel:DWORD dst_unused:UNUSED_PAD src0_sel:WORD_1
	ds_write_b128 v59, v[66:69]
	v_pk_mul_f32 v[12:13], v[2:3], v[20:21]
	v_cvt_f32_f16_sdwa v51, v48 dst_sel:DWORD dst_unused:UNUSED_PAD src0_sel:WORD_1
	v_pk_mul_f32 v[14:15], v[12:13], v[34:35] op_sel:[0,1]
	v_cvt_f32_f16_e32 v12, v47
	v_cvt_f32_f16_sdwa v13, v47 dst_sel:DWORD dst_unused:UNUSED_PAD src0_sel:WORD_1
	v_cvt_f32_f16_e32 v50, v48
	v_cvt_f32_f16_sdwa v69, v49 dst_sel:DWORD dst_unused:UNUSED_PAD src0_sel:WORD_1
	v_cvt_f32_f16_e32 v68, v49
	v_cvt_f32_f16_sdwa v67, v43 dst_sel:DWORD dst_unused:UNUSED_PAD src0_sel:WORD_1
	v_cvt_f32_f16_e32 v66, v43
	v_mul_f32_e32 v10, 0xbfb8aa3b, v10
	v_mul_f32_e32 v11, 0xbfb8aa3b, v11
	v_mul_f32_e32 v12, 0xbfb8aa3b, v12
	v_mul_f32_e32 v13, 0xbfb8aa3b, v13
	v_exp_f32_e32 v10, v10
	v_exp_f32_e32 v11, v11
	v_exp_f32_e32 v12, v12
	v_exp_f32_e32 v13, v13
	v_xor_b32_e32 v22, 0x80000000, v50
	v_xor_b32_e32 v23, 0x80000000, v51
	v_xor_b32_e32 v24, 0x80000000, v68
	v_xor_b32_e32 v25, 0x80000000, v69
	v_pk_add_f32 v[50:51], v[50:51], -1.0 op_sel_hi:[1,0]
	v_pk_add_f32 v[68:69], v[68:69], -1.0 op_sel_hi:[1,0]
	v_pk_mul_f32 v[16:17], v[4:5], v[66:67]
	v_pk_fma_f32 v[68:69], v[8:9], v[68:69], 1.0 op_sel_hi:[1,1,0]
	v_pk_fma_f32 v[50:51], v[6:7], v[50:51], 1.0 op_sel_hi:[1,1,0]
	s_cmpk_gt_u32 s25, 0x85
	v_cvt_f32_f16_sdwa v19, v44 dst_sel:DWORD dst_unused:UNUSED_PAD src0_sel:WORD_1
	v_cvt_f32_f16_e32 v18, v44
	v_pk_mul_f32 v[16:17], v[16:17], v[34:35] op_sel:[0,1]
	v_pk_mul_f32 v[68:69], v[68:69], v[66:67]
	v_pk_mul_f32 v[66:67], v[50:51], v[20:21]
	v_cvt_f32_f16_sdwa v21, v45 dst_sel:DWORD dst_unused:UNUSED_PAD src0_sel:WORD_1
	v_cvt_f32_f16_e32 v20, v45
	s_cselect_b64 s[20:21], -1, 0
	v_pk_mul_f32 v[24:25], v[16:17], v[24:25]
	v_pk_mul_f32 v[22:23], v[14:15], v[22:23]
	ds_write_b128 v55, v[10:13] offset:47104
	ds_write_b128 v55, v[14:17] offset:55296
	s_waitcnt vmcnt(0)
	v_cvt_f32_f16_sdwa v11, v65 dst_sel:DWORD dst_unused:UNUSED_PAD src0_sel:WORD_1
	v_cvt_f32_f16_e32 v10, v65
	s_and_b64 vcc, exec, s[20:21]
	ds_write_b128 v55, v[22:25] offset:63488
	ds_write_b128 v59, v[66:69] offset:4096
	ds_write_b128 v60, v[18:21] offset:4096
	ds_write2_b32 v61, v10, v11 offset1:36
	s_cbranch_vccnz .LBB0_1320
	s_mov_b32 s2, 32
	s_and_b64 vcc, exec, s[6:7]
	s_cbranch_vccnz .Lrwp_a
	s_movk_i32 s2, 0xffe0
	s_cmp_eq_u32 s25, 6
	s_cbranch_scc0 .Lrwp_a
	s_movk_i32 s2, 0x10e0

; __device__ __forceinline__ void phase_rwc(const int wvs, const Params& p, LAS unsigned char* lds, int layer, int wg0) {
;     ...
;     for (int blk = 0; blk < NBLK; ++blk) {
;       if (blk + 1 < NBLK) RW_DERIVE((blk + 1) & 1)
;       if (blk + 2 < NBLK) RW_LOAD(blk + 2)
;       if (blk >= 1) RW_YOUT(blk - 1)
;       __syncthreads();
.LBB0_1330:
	s_cmpk_eq_i32 s24, 0x10c0
	s_waitcnt lgkmcnt(0)
	s_barrier
	s_cbranch_scc1 .LBB0_1332
	s_waitcnt vmcnt(10)
	v_cvt_f32_f16_sdwa v21, v28 dst_sel:DWORD dst_unused:UNUSED_PAD src0_sel:WORD_1
	v_cvt_f32_f16_e32 v20, v28
	s_waitcnt vmcnt(7)
	v_cvt_f32_f16_sdwa v51, v36 dst_sel:DWORD dst_unused:UNUSED_PAD src0_sel:WORD_1
	v_cvt_f32_f16_e32 v50, v36
	v_cvt_f32_f16_sdwa v71, v37 dst_sel:DWORD dst_unused:UNUSED_PAD src0_sel:WORD_1
	v_pk_mul_f32 v[12:13], v[2:3], v[20:21]
	v_cvt_f32_f16_e32 v70, v37
	v_cvt_f32_f16_e32 v10, v32
	v_cvt_f32_f16_sdwa v11, v32 dst_sel:DWORD dst_unused:UNUSED_PAD src0_sel:WORD_1
	s_waitcnt vmcnt(1)
	v_pk_mul_f32 v[14:15], v[12:13], v[34:35] op_sel_hi:[1,0]
	v_cvt_f32_f16_e32 v12, v33
	v_cvt_f32_f16_sdwa v13, v33 dst_sel:DWORD dst_unused:UNUSED_PAD src0_sel:WORD_1
	v_cvt_f32_f16_sdwa v69, v29 dst_sel:DWORD dst_unused:UNUSED_PAD src0_sel:WORD_1
	v_cvt_f32_f16_e32 v68, v29
	v_xor_b32_e32 v22, 0x80000000, v50
	v_xor_b32_e32 v23, 0x80000000, v51
	v_xor_b32_e32 v24, 0x80000000, v70
	v_xor_b32_e32 v25, 0x80000000, v71
	v_pk_add_f32 v[50:51], v[50:51], -1.0 op_sel_hi:[1,0]
	v_pk_add_f32 v[70:71], v[70:71], -1.0 op_sel_hi:[1,0]
	v_mul_f32_e32 v10, 0xbfb8aa3b, v10
	v_mul_f32_e32 v11, 0xbfb8aa3b, v11
	v_mul_f32_e32 v12, 0xbfb8aa3b, v12
	v_mul_f32_e32 v13, 0xbfb8aa3b, v13
	v_pk_fma_f32 v[70:71], v[8:9], v[70:71], 1.0 op_sel_hi:[1,1,0]
	v_pk_fma_f32 v[50:51], v[6:7], v[50:51], 1.0 op_sel_hi:[1,1,0]
	v_exp_f32_e32 v10, v10
	v_exp_f32_e32 v11, v11
	v_cvt_f32_f16_sdwa v19, v30 dst_sel:DWORD dst_unused:UNUSED_PAD src0_sel:WORD_1
	v_cvt_f32_f16_e32 v18, v30
	v_exp_f32_e32 v12, v12
	v_exp_f32_e32 v13, v13
	v_pk_mul_f32 v[16:17], v[4:5], v[68:69]
	v_pk_mul_f32 v[70:71], v[70:71], v[68:69]
	v_pk_mul_f32 v[68:69], v[50:51], v[20:21]
	v_cvt_f32_f16_sdwa v21, v31 dst_sel:DWORD dst_unused:UNUSED_PAD src0_sel:WORD_1
	v_cvt_f32_f16_e32 v20, v31
	v_pk_mul_f32 v[16:17], v[16:17], v[34:35] op_sel_hi:[1,0]
	v_pk_mul_f32 v[22:23], v[14:15], v[22:23]
	v_pk_mul_f32 v[24:25], v[16:17], v[24:25]
	ds_write_b128 v55, v[10:13]
	ds_write_b128 v55, v[14:17] offset:8192
	ds_write_b128 v55, v[22:25] offset:16384
	ds_write_b128 v55, v[18:21] offset:32768
	v_cvt_f32_f16_sdwa v21, v42 dst_sel:DWORD dst_unused:UNUSED_PAD src0_sel:WORD_1
	v_cvt_f32_f16_e32 v20, v42
	v_cvt_f32_f16_e32 v10, v46
	v_cvt_f32_f16_sdwa v11, v46 dst_sel:DWORD dst_unused:UNUSED_PAD src0_sel:WORD_1
	ds_write_b128 v55, v[68:71] offset:24576
	v_pk_mul_f32 v[12:13], v[2:3], v[20:21]
	v_cvt_f32_f16_sdwa v51, v48 dst_sel:DWORD dst_unused:UNUSED_PAD src0_sel:WORD_1
	v_pk_mul_f32 v[14:15], v[12:13], v[34:35] op_sel:[0,1]
	v_cvt_f32_f16_e32 v12, v47
	v_cvt_f32_f16_sdwa v13, v47 dst_sel:DWORD dst_unused:UNUSED_PAD src0_sel:WORD_1
	v_cvt_f32_f16_e32 v50, v48
	v_cvt_f32_f16_sdwa v71, v49 dst_sel:DWORD dst_unused:UNUSED_PAD src0_sel:WORD_1
	v_cvt_f32_f16_e32 v70, v49
	v_cvt_f32_f16_sdwa v69, v43 dst_sel:DWORD dst_unused:UNUSED_PAD src0_sel:WORD_1
	v_cvt_f32_f16_e32 v68, v43
	v_mul_f32_e32 v10, 0xbfb8aa3b, v10
	v_mul_f32_e32 v11, 0xbfb8aa3b, v11
	v_mul_f32_e32 v12, 0xbfb8aa3b, v12
	v_mul_f32_e32 v13, 0xbfb8aa3b, v13
	v_exp_f32_e32 v10, v10
	v_exp_f32_e32 v11, v11
	v_exp_f32_e32 v12, v12
	v_exp_f32_e32 v13, v13
	v_xor_b32_e32 v22, 0x80000000, v50
	v_xor_b32_e32 v23, 0x80000000, v51
	v_xor_b32_e32 v24, 0x80000000, v70
	v_xor_b32_e32 v25, 0x80000000, v71
	v_pk_add_f32 v[50:51], v[50:51], -1.0 op_sel_hi:[1,0]
	v_pk_add_f32 v[70:71], v[70:71], -1.0 op_sel_hi:[1,0]
	v_pk_mul_f32 v[16:17], v[4:5], v[68:69]
	v_pk_fma_f32 v[70:71], v[8:9], v[70:71], 1.0 op_sel_hi:[1,1,0]
	v_pk_fma_f32 v[50:51], v[6:7], v[50:51], 1.0 op_sel_hi:[1,1,0]
	v_cvt_f32_f16_sdwa v19, v44 dst_sel:DWORD dst_unused:UNUSED_PAD src0_sel:WORD_1
	v_cvt_f32_f16_e32 v18, v44
	v_pk_mul_f32 v[16:17], v[16:17], v[34:35] op_sel:[0,1]
	v_pk_mul_f32 v[70:71], v[70:71], v[68:69]
	v_pk_mul_f32 v[68:69], v[50:51], v[20:21]
	v_cvt_f32_f16_sdwa v21, v45 dst_sel:DWORD dst_unused:UNUSED_PAD src0_sel:WORD_1
	v_cvt_f32_f16_e32 v20, v45
	v_pk_mul_f32 v[24:25], v[16:17], v[24:25]
	v_pk_mul_f32 v[22:23], v[14:15], v[22:23]
	ds_write_b128 v55, v[10:13] offset:4096
	ds_write_b128 v55, v[14:17] offset:12288
	s_waitcnt vmcnt(0)
	v_cvt_f32_f16_sdwa v11, v65 dst_sel:DWORD dst_unused:UNUSED_PAD src0_sel:WORD_1
	v_cvt_f32_f16_e32 v10, v65
	ds_write_b128 v55, v[22:25] offset:20480
	ds_write_b128 v55, v[68:71] offset:28672
	ds_write_b128 v55, v[18:21] offset:36864
	ds_write2_b32 v56, v10, v11 offset1:36
